# ssd_s3 per-tile part: C-conv taps of all four k-slices and the PREV state fragments fetched in batches ahead of use (were load-and-wait one by one); MFMA-to-VALU spacing kept
# speedup vs baseline: 1.0231x; 1.0010x over previous
.LBB0_2295:
	v_lshlrev_b32_e32 v52, 4, v75
	v_or_b32_e32 v120, v52, v71
	v_ashrrev_i32_e32 v121, 31, v120
	v_lshl_add_u64 v[116:117], s[92:93], 0, v[120:121]
	v_mov_b64_e32 v[2:3], s[76:77]
	v_mad_u64_u32 v[118:119], s[4:5], v116, s64, v[2:3]
	v_mov_b32_e32 v2, v119
	v_mad_u64_u32 v[2:3], s[4:5], v117, s64, v[2:3]
	v_mov_b32_e32 v119, v2
	v_lshl_add_u64 v[2:3], v[118:119], 0, s[48:49]
	v_lshl_add_u64 v[2:3], v[2:3], 0, v[82:83]
	s_mov_b64 s[4:5], 0x1400
	v_add_u32_e32 v50, s82, v130
	v_lshl_add_u64 v[48:49], v[2:3], 0, s[4:5]
	s_waitcnt vmcnt(2)
	ds_read_b128 v[32:35], v50 offset:512
	ds_read_b128 v[28:31], v50 offset:528
	ds_read_b128 v[24:27], v50 offset:1024
	ds_read_b128 v[20:23], v50 offset:1040
	ds_read_b128 v[16:19], v50 offset:1536
	ds_read_b128 v[12:15], v50 offset:1552
	ds_read_b128 v[6:9], v131
	ds_read_b128 v[2:5], v131 offset:16
	s_waitcnt vmcnt(1)
	s_mov_b32 s50, 0xffffc800
	s_mov_b32 s51, -1
	s_mov_b32 s98, 0xfffff800
	s_mov_b32 s99, -1
	v_lshl_add_u64 v[234:235], v[48:49], 0, s[50:51]
	v_lshl_add_u64 v[236:237], v[48:49], 0, s[98:99]
	global_load_dwordx4 v[150:153], v[234:235], off offset:-4096
	global_load_dwordx4 v[154:157], v[234:235], off offset:2048
	global_load_dwordx4 v[158:161], v[236:237], off offset:-4096
	global_load_dwordx4 v[162:165], v[236:237], off offset:2048
	global_load_dwordx4 v[166:169], v[234:235], off offset:-4032
	global_load_dwordx4 v[170:173], v[234:235], off offset:2112
	global_load_dwordx4 v[182:185], v[236:237], off offset:-4032
	global_load_dwordx4 v[186:189], v[236:237], off offset:2112
	global_load_dwordx4 v[190:193], v[234:235], off offset:-3968
	global_load_dwordx4 v[194:197], v[234:235], off offset:2176
	global_load_dwordx4 v[198:201], v[236:237], off offset:-3968
	global_load_dwordx4 v[214:217], v[236:237], off offset:2176
	global_load_dwordx4 v[218:221], v[234:235], off offset:-3904
	global_load_dwordx4 v[222:225], v[234:235], off offset:2240
	global_load_dwordx4 v[226:229], v[236:237], off offset:-3904
	global_load_dwordx4 v[230:233], v[236:237], off offset:2240
	v_add_u32_e32 v36, s55, v120
	v_cmp_lt_i32_e64 s[16:17], 2, v36
	s_and_saveexec_b64 s[18:19], s[16:17]
	s_cbranch_execnz .LBB0_2350
	s_or_b64 exec, exec, s[18:19]
	v_cmp_lt_i32_e64 s[18:19], 1, v36
	s_and_saveexec_b64 s[20:21], s[18:19]
	s_cbranch_execnz .LBB0_2351

.LBB0_2299:
	s_waitcnt vmcnt(0)
	s_waitcnt lgkmcnt(4)
	v_and_b32_e32 v25, 0xffff0000, v162
	v_lshlrev_b32_e32 v24, 16, v162
	s_waitcnt lgkmcnt(1)
	v_pk_fma_f32 v[6:7], v[16:17], v[24:25], v[6:7]
	v_and_b32_e32 v17, 0xffff0000, v163
	v_lshlrev_b32_e32 v16, 16, v163
	v_pk_fma_f32 v[8:9], v[18:19], v[16:17], v[8:9]
	v_and_b32_e32 v17, 0xffff0000, v164
	v_lshlrev_b32_e32 v16, 16, v164
	s_waitcnt lgkmcnt(0)
	v_pk_fma_f32 v[2:3], v[12:13], v[16:17], v[2:3]
	v_and_b32_e32 v13, 0xffff0000, v165
	v_lshlrev_b32_e32 v12, 16, v165
	v_pk_fma_f32 v[4:5], v[14:15], v[12:13], v[4:5]

.LBB0_2304:
	s_waitcnt vmcnt(0)
	s_waitcnt lgkmcnt(4)
	v_and_b32_e32 v29, 0xffff0000, v186
	v_lshlrev_b32_e32 v28, 16, v186
	s_waitcnt lgkmcnt(1)
	v_pk_fma_f32 v[12:13], v[20:21], v[28:29], v[12:13]
	v_and_b32_e32 v21, 0xffff0000, v187
	v_lshlrev_b32_e32 v20, 16, v187
	v_pk_fma_f32 v[14:15], v[22:23], v[20:21], v[14:15]
	v_and_b32_e32 v21, 0xffff0000, v188
	v_lshlrev_b32_e32 v20, 16, v188
	s_waitcnt lgkmcnt(0)
	v_pk_fma_f32 v[2:3], v[16:17], v[20:21], v[2:3]
	v_and_b32_e32 v17, 0xffff0000, v189
	v_lshlrev_b32_e32 v16, 16, v189
	v_pk_fma_f32 v[4:5], v[18:19], v[16:17], v[4:5]

.LBB0_2309:
	s_waitcnt vmcnt(0)
	s_waitcnt lgkmcnt(4)
	v_and_b32_e32 v33, 0xffff0000, v214
	v_lshlrev_b32_e32 v32, 16, v214
	s_waitcnt lgkmcnt(1)
	v_pk_fma_f32 v[12:13], v[20:21], v[32:33], v[12:13]
	v_and_b32_e32 v21, 0xffff0000, v215
	v_lshlrev_b32_e32 v20, 16, v215
	v_pk_fma_f32 v[14:15], v[22:23], v[20:21], v[14:15]
	v_and_b32_e32 v21, 0xffff0000, v216
	v_lshlrev_b32_e32 v20, 16, v216
	s_waitcnt lgkmcnt(0)
	v_pk_fma_f32 v[2:3], v[16:17], v[20:21], v[2:3]
	v_and_b32_e32 v17, 0xffff0000, v217
	v_lshlrev_b32_e32 v16, 16, v217
	v_pk_fma_f32 v[4:5], v[18:19], v[16:17], v[4:5]

.LBB0_2314:
	s_waitcnt vmcnt(0)
	s_waitcnt lgkmcnt(4)
	v_and_b32_e32 v37, 0xffff0000, v230
	v_lshlrev_b32_e32 v36, 16, v230
	s_waitcnt lgkmcnt(1)
	v_pk_fma_f32 v[12:13], v[20:21], v[36:37], v[12:13]
	v_and_b32_e32 v21, 0xffff0000, v231
	v_lshlrev_b32_e32 v20, 16, v231
	v_pk_fma_f32 v[14:15], v[22:23], v[20:21], v[14:15]
	v_and_b32_e32 v21, 0xffff0000, v232
	v_lshlrev_b32_e32 v20, 16, v232
	s_waitcnt lgkmcnt(0)
	v_pk_fma_f32 v[2:3], v[16:17], v[20:21], v[2:3]
	v_and_b32_e32 v17, 0xffff0000, v233
	v_lshlrev_b32_e32 v16, 16, v233
	v_pk_fma_f32 v[4:5], v[18:19], v[16:17], v[4:5]
.LBB0_2315:
	s_or_b64 exec, exec, s[16:17]
	global_load_dwordx4 v[150:153], v[86:87], off
	global_load_dwordx4 v[154:157], v[86:87], off offset:64
	global_load_dwordx4 v[158:161], v[86:87], off offset:128
	global_load_dwordx4 v[162:165], v[86:87], off offset:192
	global_load_dwordx4 v[166:169], v[88:89], off
	global_load_dwordx4 v[170:173], v[88:89], off offset:64
	global_load_dwordx4 v[182:185], v[88:89], off offset:128
	global_load_dwordx4 v[186:189], v[88:89], off offset:192
	global_load_dwordx4 v[190:193], v[90:91], off
	global_load_dwordx4 v[194:197], v[90:91], off offset:64
	global_load_dwordx4 v[198:201], v[90:91], off offset:128
	global_load_dwordx4 v[214:217], v[90:91], off offset:192
	global_load_dwordx4 v[218:221], v[92:93], off
	global_load_dwordx4 v[222:225], v[92:93], off offset:64
	global_load_dwordx4 v[226:229], v[92:93], off offset:128
	global_load_dwordx4 v[230:233], v[92:93], off offset:192
	s_waitcnt lgkmcnt(1)
	v_mul_f32_e32 v16, 0xbfb8aa3b, v12
	v_exp_f32_e32 v16, v16
	v_lshl_add_u32 v77, v120, 2, 0
	v_or_b32_e32 v52, 15, v52
	v_cmp_lt_i32_e32 vcc, s65, v52
	v_add_f32_e32 v16, 1.0, v16
	v_rcp_f32_e32 v16, v16
	s_nop 0
	s_nop 0
	v_mul_f32_e32 v12, v12, v16
	v_mul_f32_e32 v16, 0xbfb8aa3b, v13
	v_exp_f32_e32 v16, v16
	s_nop 0
	v_add_f32_e32 v16, 1.0, v16
	v_rcp_f32_e32 v16, v16
	s_nop 0
	v_mul_f32_e32 v13, v13, v16
	v_mul_f32_e32 v16, 0xbfb8aa3b, v14
	v_exp_f32_e32 v16, v16
	v_cvt_pk_bf16_f32 v44, v12, v13
	s_nop 0
	v_add_f32_e32 v16, 1.0, v16
	v_rcp_f32_e32 v16, v16
	s_nop 0
	v_mul_f32_e32 v14, v14, v16
	v_mul_f32_e32 v16, 0xbfb8aa3b, v15
	v_exp_f32_e32 v16, v16
	s_nop 0
	v_add_f32_e32 v16, 1.0, v16
	v_rcp_f32_e32 v16, v16
	s_nop 0
	v_mul_f32_e32 v15, v15, v16
	s_waitcnt lgkmcnt(0)
	v_mul_f32_e32 v16, 0xbfb8aa3b, v2
	v_exp_f32_e32 v16, v16
	v_cvt_pk_bf16_f32 v45, v14, v15
	s_nop 0
	v_add_f32_e32 v16, 1.0, v16
	v_rcp_f32_e32 v16, v16
	s_nop 0
	v_mul_f32_e32 v2, v2, v16
	v_mul_f32_e32 v16, 0xbfb8aa3b, v3
	v_exp_f32_e32 v16, v16
	s_nop 0
	v_add_f32_e32 v16, 1.0, v16
	v_rcp_f32_e32 v16, v16
	s_nop 0
	v_mul_f32_e32 v3, v3, v16
	v_mul_f32_e32 v16, 0xbfb8aa3b, v4
	v_exp_f32_e32 v16, v16
	v_cvt_pk_bf16_f32 v46, v2, v3
	v_add_u32_e32 v2, 0x21800, v77
	ds_read2st64_b32 v[122:123], v2 offset1:4
	v_add_f32_e32 v16, 1.0, v16
	v_rcp_f32_e32 v16, v16
	s_waitcnt lgkmcnt(0)
	v_mul_f32_e32 v2, 0x3fb8aa3b, v122
	v_mul_f32_e32 v4, v4, v16
	v_mul_f32_e32 v16, 0xbfb8aa3b, v5
	v_exp_f32_e32 v16, v16
	v_exp_f32_e32 v2, v2
	v_add_f32_e32 v16, 1.0, v16
	v_rcp_f32_e32 v16, v16
	s_nop 0
	v_mul_f32_e32 v5, v5, v16
	s_nop 0
	s_nop 0
	s_waitcnt vmcnt(15)
	v_mfma_f32_16x16x32_bf16 v[12:15], v[150:153], v[6:9], 0
	v_cvt_pk_bf16_f32 v47, v4, v5
	s_nop 0
	s_waitcnt vmcnt(14)
	v_mfma_f32_16x16x32_bf16 v[12:15], v[154:157], v[24:27], v[12:15]
	s_nop 0
	s_nop 0
	s_waitcnt vmcnt(13)
	v_mfma_f32_16x16x32_bf16 v[12:15], v[158:161], v[28:31], v[12:15]
	s_nop 0
	s_nop 0
	s_waitcnt vmcnt(12)
	v_mfma_f32_16x16x32_bf16 v[12:15], v[162:165], v[44:47], v[12:15]
	s_nop 0
	s_nop 6
	v_pk_mul_f32 v[50:51], v[2:3], v[14:15] op_sel_hi:[0,1]
	v_pk_mul_f32 v[48:49], v[2:3], v[12:13] op_sel_hi:[0,1]
	s_nop 0
	s_nop 0
	s_waitcnt vmcnt(11)
	v_mfma_f32_16x16x32_bf16 v[12:15], v[166:169], v[6:9], 0
	s_waitcnt vmcnt(10)
	v_mfma_f32_16x16x32_bf16 v[12:15], v[170:173], v[24:27], v[12:15]
	s_nop 0
	s_nop 0
	s_waitcnt vmcnt(9)
	v_mfma_f32_16x16x32_bf16 v[12:15], v[182:185], v[28:31], v[12:15]
	s_nop 0
	s_nop 0
	s_waitcnt vmcnt(8)
	v_mfma_f32_16x16x32_bf16 v[12:15], v[186:189], v[44:47], v[12:15]
	s_nop 0
	s_nop 6
	v_pk_mul_f32 v[42:43], v[2:3], v[14:15] op_sel_hi:[0,1]
	v_pk_mul_f32 v[40:41], v[2:3], v[12:13] op_sel_hi:[0,1]
	s_nop 0
	s_nop 0
	s_waitcnt vmcnt(7)
	v_mfma_f32_16x16x32_bf16 v[12:15], v[190:193], v[6:9], 0
	s_waitcnt vmcnt(6)
	v_mfma_f32_16x16x32_bf16 v[12:15], v[194:197], v[24:27], v[12:15]
	s_nop 0
	s_nop 0
	s_waitcnt vmcnt(5)
	v_mfma_f32_16x16x32_bf16 v[12:15], v[198:201], v[28:31], v[12:15]
	s_nop 0
	s_nop 0
	s_waitcnt vmcnt(4)
	v_mfma_f32_16x16x32_bf16 v[12:15], v[214:217], v[44:47], v[12:15]
	s_nop 0
	s_nop 6
	v_pk_mul_f32 v[38:39], v[2:3], v[14:15] op_sel_hi:[0,1]
	v_pk_mul_f32 v[36:37], v[2:3], v[12:13] op_sel_hi:[0,1]
	s_nop 0
	s_nop 0
	s_waitcnt vmcnt(3)
	v_mfma_f32_16x16x32_bf16 v[12:15], v[218:221], v[6:9], 0
	s_waitcnt vmcnt(2)
	v_mfma_f32_16x16x32_bf16 v[12:15], v[222:225], v[24:27], v[12:15]
	s_nop 0
	s_nop 0
	s_waitcnt vmcnt(1)
	v_mfma_f32_16x16x32_bf16 v[12:15], v[226:229], v[28:31], v[12:15]
	s_nop 0
	s_nop 0
	s_waitcnt vmcnt(0)
	v_mfma_f32_16x16x32_bf16 v[12:15], v[230:233], v[44:47], v[12:15]
	global_load_dwordx4 v[150:153], v[94:95], off
	global_load_dwordx4 v[154:157], v[94:95], off offset:64
	global_load_dwordx4 v[158:161], v[94:95], off offset:128
	global_load_dwordx4 v[162:165], v[94:95], off offset:192
	global_load_dwordx4 v[166:169], v[96:97], off
	global_load_dwordx4 v[170:173], v[96:97], off offset:64
	global_load_dwordx4 v[182:185], v[96:97], off offset:128
	global_load_dwordx4 v[186:189], v[96:97], off offset:192
	global_load_dwordx4 v[190:193], v[98:99], off
	global_load_dwordx4 v[194:197], v[98:99], off offset:64
	global_load_dwordx4 v[198:201], v[98:99], off offset:128
	global_load_dwordx4 v[214:217], v[98:99], off offset:192
	global_load_dwordx4 v[218:221], v[100:101], off
	global_load_dwordx4 v[222:225], v[100:101], off offset:64
	global_load_dwordx4 v[226:229], v[100:101], off offset:128
	global_load_dwordx4 v[230:233], v[100:101], off offset:192
	s_nop 0
	s_nop 6
	v_pk_mul_f32 v[34:35], v[2:3], v[14:15] op_sel_hi:[0,1]
	v_pk_mul_f32 v[32:33], v[2:3], v[12:13] op_sel_hi:[0,1]
	s_nop 0
	v_mul_f32_e32 v2, 0x3fb8aa3b, v123
	v_exp_f32_e32 v2, v2
	s_nop 0
	s_waitcnt vmcnt(15)
	v_mfma_f32_16x16x32_bf16 v[12:15], v[150:153], v[6:9], 0
	s_waitcnt vmcnt(14)
	v_mfma_f32_16x16x32_bf16 v[12:15], v[154:157], v[24:27], v[12:15]
	s_nop 0
	s_nop 0
	s_waitcnt vmcnt(13)
	v_mfma_f32_16x16x32_bf16 v[12:15], v[158:161], v[28:31], v[12:15]
	s_nop 0
	s_nop 0
	s_waitcnt vmcnt(12)
	v_mfma_f32_16x16x32_bf16 v[12:15], v[162:165], v[44:47], v[12:15]
	s_nop 0
	s_nop 6
	v_pk_mul_f32 v[22:23], v[2:3], v[14:15] op_sel_hi:[0,1]
	v_pk_mul_f32 v[20:21], v[2:3], v[12:13] op_sel_hi:[0,1]
	s_nop 0
	s_nop 0
	s_waitcnt vmcnt(11)
	v_mfma_f32_16x16x32_bf16 v[12:15], v[166:169], v[6:9], 0
	s_waitcnt vmcnt(10)
	v_mfma_f32_16x16x32_bf16 v[12:15], v[170:173], v[24:27], v[12:15]
	s_nop 0
	s_nop 0
	s_waitcnt vmcnt(9)
	v_mfma_f32_16x16x32_bf16 v[12:15], v[182:185], v[28:31], v[12:15]
	s_nop 0
	s_nop 0
	s_waitcnt vmcnt(8)
	v_mfma_f32_16x16x32_bf16 v[12:15], v[186:189], v[44:47], v[12:15]
	s_nop 7
	v_pk_mul_f32 v[18:19], v[2:3], v[14:15] op_sel_hi:[0,1]
	v_pk_mul_f32 v[16:17], v[2:3], v[12:13] op_sel_hi:[0,1]
	s_nop 0
	s_nop 0
	s_waitcnt vmcnt(7)
	v_mfma_f32_16x16x32_bf16 v[12:15], v[190:193], v[6:9], 0
	s_waitcnt vmcnt(6)
	v_mfma_f32_16x16x32_bf16 v[12:15], v[194:197], v[24:27], v[12:15]
	s_nop 0
	s_nop 0
	s_waitcnt vmcnt(5)
	v_mfma_f32_16x16x32_bf16 v[12:15], v[198:201], v[28:31], v[12:15]
	s_nop 0
	s_nop 0
	s_waitcnt vmcnt(4)
	v_mfma_f32_16x16x32_bf16 v[12:15], v[214:217], v[44:47], v[12:15]
	s_nop 0
	s_nop 6
	v_pk_mul_f32 v[14:15], v[2:3], v[14:15] op_sel_hi:[0,1]
	v_pk_mul_f32 v[12:13], v[2:3], v[12:13] op_sel_hi:[0,1]
	s_nop 0
	s_waitcnt vmcnt(3)
	v_mfma_f32_16x16x32_bf16 v[54:57], v[218:221], v[6:9], 0
	s_waitcnt vmcnt(2)
	v_mfma_f32_16x16x32_bf16 v[54:57], v[222:225], v[24:27], v[54:57]
	s_nop 0
	s_nop 0
	s_waitcnt vmcnt(1)
	v_mfma_f32_16x16x32_bf16 v[54:57], v[226:229], v[28:31], v[54:57]
	s_nop 0
	s_nop 0
	s_waitcnt vmcnt(0)
	v_mfma_f32_16x16x32_bf16 v[54:57], v[230:233], v[44:47], v[54:57]
	s_nop 7
	v_pk_mul_f32 v[4:5], v[2:3], v[56:57] op_sel_hi:[0,1]
	v_pk_mul_f32 v[2:3], v[2:3], v[54:55] op_sel_hi:[0,1]
	s_and_saveexec_b64 s[30:31], vcc
	s_cbranch_execz .LBB0_2294
	v_ashrrev_i32_e32 v53, 31, v52
	v_lshrrev_b32_e32 v53, 27, v53
	v_add_u32_e32 v52, v52, v53
	v_ashrrev_i32_e32 v52, 5, v52
	v_add_u32_e32 v79, 1, v52
	s_mov_b64 s[96:97], 0
	v_mov_b32_e32 v81, v142
	v_mov_b32_e32 v103, v141
	v_mov_b32_e32 v105, v139
	v_mov_b32_e32 v107, v140
	s_branch .LBB0_2318

.LBB0_2350:
	s_waitcnt vmcnt(0)
	v_add_u32_e32 v37, 0, v130
	v_add_u32_e32 v37, 0x22800, v37
	s_nop 0
	s_waitcnt vmcnt(0)
	ds_read_b128 v[38:41], v37
	ds_read_b128 v[42:45], v37 offset:16
	v_and_b32_e32 v47, 0xffff0000, v150
	v_lshlrev_b32_e32 v46, 16, v150
	s_waitcnt lgkmcnt(1)
	v_pk_fma_f32 v[6:7], v[38:39], v[46:47], v[6:7]
	v_and_b32_e32 v39, 0xffff0000, v151
	v_lshlrev_b32_e32 v38, 16, v151
	v_pk_fma_f32 v[8:9], v[40:41], v[38:39], v[8:9]
	v_and_b32_e32 v39, 0xffff0000, v152
	v_lshlrev_b32_e32 v38, 16, v152
	s_waitcnt lgkmcnt(0)
	v_pk_fma_f32 v[2:3], v[42:43], v[38:39], v[2:3]
	v_and_b32_e32 v39, 0xffff0000, v153
	v_lshlrev_b32_e32 v38, 16, v153
	v_pk_fma_f32 v[4:5], v[44:45], v[38:39], v[4:5]
	s_or_b64 exec, exec, s[18:19]
	v_cmp_lt_i32_e64 s[18:19], 1, v36
	s_and_saveexec_b64 s[20:21], s[18:19]
	s_cbranch_execz .LBB0_2297
.LBB0_2351:
	s_waitcnt vmcnt(0)
	s_nop 1
	v_and_b32_e32 v43, 0xffff0000, v154
	v_lshlrev_b32_e32 v42, 16, v154
	s_waitcnt lgkmcnt(1)
	v_pk_fma_f32 v[6:7], v[32:33], v[42:43], v[6:7]
	v_and_b32_e32 v33, 0xffff0000, v155
	v_lshlrev_b32_e32 v32, 16, v155
	v_pk_fma_f32 v[8:9], v[34:35], v[32:33], v[8:9]
	v_and_b32_e32 v33, 0xffff0000, v156
	v_lshlrev_b32_e32 v32, 16, v156
	s_waitcnt lgkmcnt(0)
	v_pk_fma_f32 v[2:3], v[28:29], v[32:33], v[2:3]
	v_and_b32_e32 v29, 0xffff0000, v157
	v_lshlrev_b32_e32 v28, 16, v157
	v_pk_fma_f32 v[4:5], v[30:31], v[28:29], v[4:5]
	s_or_b64 exec, exec, s[20:21]
	v_cmp_lt_i32_e64 s[20:21], 0, v36
	s_and_saveexec_b64 s[22:23], s[20:21]
	s_cbranch_execz .LBB0_2298
.LBB0_2352:
	s_waitcnt vmcnt(0)
	s_waitcnt lgkmcnt(6)
	s_nop 1
	v_and_b32_e32 v33, 0xffff0000, v158
	v_lshlrev_b32_e32 v32, 16, v158
	s_waitcnt lgkmcnt(1)
	v_pk_fma_f32 v[6:7], v[24:25], v[32:33], v[6:7]
	v_and_b32_e32 v25, 0xffff0000, v159
	v_lshlrev_b32_e32 v24, 16, v159
	v_pk_fma_f32 v[8:9], v[26:27], v[24:25], v[8:9]
	v_and_b32_e32 v25, 0xffff0000, v160
	v_lshlrev_b32_e32 v24, 16, v160
	s_waitcnt lgkmcnt(0)
	v_pk_fma_f32 v[2:3], v[20:21], v[24:25], v[2:3]
	v_and_b32_e32 v21, 0xffff0000, v161
	v_lshlrev_b32_e32 v20, 16, v161
	v_pk_fma_f32 v[4:5], v[22:23], v[20:21], v[4:5]
	s_or_b64 exec, exec, s[22:23]
	v_cmp_lt_i32_e64 s[22:23], -1, v36
	s_and_saveexec_b64 s[24:25], s[22:23]
	s_cbranch_execnz .LBB0_2299
	s_branch .LBB0_2300
.LBB0_2353:
	s_waitcnt vmcnt(0)
	s_waitcnt vmcnt(0)
	ds_read_b128 v[40:43], v50 offset:128
	ds_read_b128 v[44:47], v50 offset:144
	v_and_b32_e32 v59, 0xffff0000, v166
	v_lshlrev_b32_e32 v58, 16, v166
	s_waitcnt lgkmcnt(1)
	v_pk_fma_f32 v[12:13], v[40:41], v[58:59], v[12:13]
	v_and_b32_e32 v41, 0xffff0000, v167
	v_lshlrev_b32_e32 v40, 16, v167
	v_pk_fma_f32 v[14:15], v[42:43], v[40:41], v[14:15]
	v_and_b32_e32 v41, 0xffff0000, v168
	v_lshlrev_b32_e32 v40, 16, v168
	s_waitcnt lgkmcnt(0)
	v_pk_fma_f32 v[2:3], v[44:45], v[40:41], v[2:3]
	v_and_b32_e32 v41, 0xffff0000, v169
	v_lshlrev_b32_e32 v40, 16, v169
	v_pk_fma_f32 v[4:5], v[46:47], v[40:41], v[4:5]
	s_or_b64 exec, exec, s[24:25]
	s_and_saveexec_b64 s[24:25], s[18:19]
	s_cbranch_execz .LBB0_2302
.LBB0_2354:
	s_waitcnt vmcnt(0)
	s_waitcnt vmcnt(0)
	s_nop 1
	v_and_b32_e32 v45, 0xffff0000, v170
	v_lshlrev_b32_e32 v44, 16, v170
	s_waitcnt lgkmcnt(1)
	v_pk_fma_f32 v[12:13], v[36:37], v[44:45], v[12:13]
	v_and_b32_e32 v37, 0xffff0000, v171
	v_lshlrev_b32_e32 v36, 16, v171
	v_pk_fma_f32 v[14:15], v[38:39], v[36:37], v[14:15]
	v_and_b32_e32 v37, 0xffff0000, v172
	v_lshlrev_b32_e32 v36, 16, v172
	s_waitcnt lgkmcnt(0)
	v_pk_fma_f32 v[2:3], v[32:33], v[36:37], v[2:3]
	v_and_b32_e32 v33, 0xffff0000, v173
	v_lshlrev_b32_e32 v32, 16, v173
	v_pk_fma_f32 v[4:5], v[34:35], v[32:33], v[4:5]
	s_or_b64 exec, exec, s[24:25]
	s_and_saveexec_b64 s[24:25], s[20:21]
	s_cbranch_execz .LBB0_2303
.LBB0_2355:
	s_waitcnt vmcnt(0)
	s_waitcnt lgkmcnt(6)
	s_nop 1
	v_and_b32_e32 v37, 0xffff0000, v182
	v_lshlrev_b32_e32 v36, 16, v182
	s_waitcnt lgkmcnt(1)
	v_pk_fma_f32 v[12:13], v[28:29], v[36:37], v[12:13]
	v_and_b32_e32 v29, 0xffff0000, v183
	v_lshlrev_b32_e32 v28, 16, v183
	v_pk_fma_f32 v[14:15], v[30:31], v[28:29], v[14:15]
	v_and_b32_e32 v29, 0xffff0000, v184
	v_lshlrev_b32_e32 v28, 16, v184
	s_waitcnt lgkmcnt(0)
	v_pk_fma_f32 v[2:3], v[24:25], v[28:29], v[2:3]
	v_and_b32_e32 v25, 0xffff0000, v185
	v_lshlrev_b32_e32 v24, 16, v185
	v_pk_fma_f32 v[4:5], v[26:27], v[24:25], v[4:5]
	s_or_b64 exec, exec, s[24:25]
	s_and_saveexec_b64 s[24:25], s[22:23]
	s_cbranch_execnz .LBB0_2304
	s_branch .LBB0_2305
.LBB0_2356:
	s_waitcnt vmcnt(0)
	ds_read_b128 v[44:47], v50 offset:256
	ds_read_b128 v[54:57], v50 offset:272
	v_and_b32_e32 v63, 0xffff0000, v190
	v_lshlrev_b32_e32 v62, 16, v190
	s_waitcnt lgkmcnt(1)
	v_pk_fma_f32 v[12:13], v[44:45], v[62:63], v[12:13]
	v_and_b32_e32 v45, 0xffff0000, v191
	v_lshlrev_b32_e32 v44, 16, v191
	v_pk_fma_f32 v[14:15], v[46:47], v[44:45], v[14:15]
	v_and_b32_e32 v45, 0xffff0000, v192
	v_lshlrev_b32_e32 v44, 16, v192
	s_waitcnt lgkmcnt(0)
	v_pk_fma_f32 v[2:3], v[54:55], v[44:45], v[2:3]
	v_and_b32_e32 v45, 0xffff0000, v193
	v_lshlrev_b32_e32 v44, 16, v193
	v_pk_fma_f32 v[4:5], v[56:57], v[44:45], v[4:5]
	s_or_b64 exec, exec, s[24:25]
	s_and_saveexec_b64 s[24:25], s[18:19]
	s_cbranch_execz .LBB0_2307
.LBB0_2357:
	s_waitcnt vmcnt(0)
	s_nop 1
	v_and_b32_e32 v55, 0xffff0000, v194
	v_lshlrev_b32_e32 v54, 16, v194
	s_waitcnt lgkmcnt(1)
	v_pk_fma_f32 v[12:13], v[40:41], v[54:55], v[12:13]
	v_and_b32_e32 v41, 0xffff0000, v195
	v_lshlrev_b32_e32 v40, 16, v195
	v_pk_fma_f32 v[14:15], v[42:43], v[40:41], v[14:15]
	v_and_b32_e32 v41, 0xffff0000, v196
	v_lshlrev_b32_e32 v40, 16, v196
	s_waitcnt lgkmcnt(0)
	v_pk_fma_f32 v[2:3], v[36:37], v[40:41], v[2:3]
	v_and_b32_e32 v37, 0xffff0000, v197
	v_lshlrev_b32_e32 v36, 16, v197
	v_pk_fma_f32 v[4:5], v[38:39], v[36:37], v[4:5]
	s_or_b64 exec, exec, s[24:25]
	s_and_saveexec_b64 s[24:25], s[20:21]
	s_cbranch_execz .LBB0_2308
.LBB0_2358:
	s_waitcnt vmcnt(0)
	s_waitcnt lgkmcnt(6)
	s_nop 1
	v_and_b32_e32 v41, 0xffff0000, v198
	v_lshlrev_b32_e32 v40, 16, v198
	s_waitcnt lgkmcnt(1)
	v_pk_fma_f32 v[12:13], v[32:33], v[40:41], v[12:13]
	v_and_b32_e32 v33, 0xffff0000, v199
	v_lshlrev_b32_e32 v32, 16, v199
	v_pk_fma_f32 v[14:15], v[34:35], v[32:33], v[14:15]
	v_and_b32_e32 v33, 0xffff0000, v200
	v_lshlrev_b32_e32 v32, 16, v200
	s_waitcnt lgkmcnt(0)
	v_pk_fma_f32 v[2:3], v[28:29], v[32:33], v[2:3]
	v_and_b32_e32 v29, 0xffff0000, v201
	v_lshlrev_b32_e32 v28, 16, v201
	v_pk_fma_f32 v[4:5], v[30:31], v[28:29], v[4:5]
	s_or_b64 exec, exec, s[24:25]
	s_and_saveexec_b64 s[24:25], s[22:23]
	s_cbranch_execnz .LBB0_2309
	s_branch .LBB0_2310
.LBB0_2359:
	s_waitcnt vmcnt(0)
	ds_read_b128 v[54:57], v50 offset:384
	ds_read_b128 v[58:61], v50 offset:400
	s_nop 1
	v_and_b32_e32 v51, 0xffff0000, v218
	v_lshlrev_b32_e32 v50, 16, v218
	s_waitcnt lgkmcnt(1)
	v_pk_fma_f32 v[12:13], v[54:55], v[50:51], v[12:13]
	v_and_b32_e32 v51, 0xffff0000, v219
	v_lshlrev_b32_e32 v50, 16, v219
	v_pk_fma_f32 v[14:15], v[56:57], v[50:51], v[14:15]
	v_and_b32_e32 v51, 0xffff0000, v220
	v_lshlrev_b32_e32 v50, 16, v220
	s_waitcnt lgkmcnt(0)
	v_pk_fma_f32 v[2:3], v[58:59], v[50:51], v[2:3]
	v_and_b32_e32 v51, 0xffff0000, v221
	v_lshlrev_b32_e32 v50, 16, v221
	v_pk_fma_f32 v[4:5], v[60:61], v[50:51], v[4:5]
	s_or_b64 exec, exec, s[24:25]
	s_and_saveexec_b64 s[16:17], s[18:19]
	s_cbranch_execz .LBB0_2312
.LBB0_2360:
	s_waitcnt vmcnt(0)
	s_nop 1
	v_and_b32_e32 v51, 0xffff0000, v222
	v_lshlrev_b32_e32 v50, 16, v222
	s_waitcnt lgkmcnt(1)
	v_pk_fma_f32 v[12:13], v[44:45], v[50:51], v[12:13]
	v_and_b32_e32 v45, 0xffff0000, v223
	v_lshlrev_b32_e32 v44, 16, v223
	v_pk_fma_f32 v[14:15], v[46:47], v[44:45], v[14:15]
	v_and_b32_e32 v45, 0xffff0000, v224
	v_lshlrev_b32_e32 v44, 16, v224
	s_waitcnt lgkmcnt(0)
	v_pk_fma_f32 v[2:3], v[40:41], v[44:45], v[2:3]
	v_and_b32_e32 v41, 0xffff0000, v225
	v_lshlrev_b32_e32 v40, 16, v225
	v_pk_fma_f32 v[4:5], v[42:43], v[40:41], v[4:5]
	s_or_b64 exec, exec, s[16:17]
	s_and_saveexec_b64 s[16:17], s[20:21]
	s_cbranch_execz .LBB0_2313
.LBB0_2361:
	s_waitcnt vmcnt(0)
	s_waitcnt lgkmcnt(6)
	s_nop 1
	v_and_b32_e32 v45, 0xffff0000, v226
	v_lshlrev_b32_e32 v44, 16, v226
	s_waitcnt lgkmcnt(1)
	v_pk_fma_f32 v[12:13], v[36:37], v[44:45], v[12:13]
	v_and_b32_e32 v37, 0xffff0000, v227
	v_lshlrev_b32_e32 v36, 16, v227
	v_pk_fma_f32 v[14:15], v[38:39], v[36:37], v[14:15]
	v_and_b32_e32 v37, 0xffff0000, v228
	v_lshlrev_b32_e32 v36, 16, v228
	s_waitcnt lgkmcnt(0)
	v_pk_fma_f32 v[2:3], v[32:33], v[36:37], v[2:3]
	v_and_b32_e32 v33, 0xffff0000, v229
	v_lshlrev_b32_e32 v32, 16, v229
	v_pk_fma_f32 v[4:5], v[34:35], v[32:33], v[4:5]
	s_or_b64 exec, exec, s[16:17]
	s_and_saveexec_b64 s[16:17], s[22:23]
	s_cbranch_execnz .LBB0_2314
	s_branch .LBB0_2315
